# version 97 plus gate|up and in-proj: leading half starts its epilogue without waiting for the trailing half's last MFMA block (trailing half skips the last loop barrier instead)
# baseline (speedup 1.0000x reference)
; template <class Epi, class Sched, bool ALIGN_EPI = false, bool SP2 = false>
; __device__ __forceinline__ void gemm_phase(PG8_LAS unsigned char* lds, const Gemm g, const Sched& S, const Epi& E, const int tid_in) {
;     ...
;             PG8_WAIT_V(8); PG8_WAIT_L(0); PG8_BAR; PG8_MMA(0, 0, At, B0); PG8_MMA(0, 1, At, B1); PG8_BAR; PG8_SCHED;
;             PG8_LDA(At, 1, 1); PG8_STAGE(PG8_SB(1, 0), b3, voffB); PG8_STAGE(PG8_SB(1, 1), b3 + hstep, voffB); PG8_STAGE(PG8_SA(1, 0), a3, voffA);
;             PG8_WAIT_V(8); PG8_WAIT_L(0); PG8_BAR; PG8_MMA(1, 0, At, B0); PG8_MMA(1, 1, At, B1); PG8_BAR; PG8_SCHED;
;             } else {
;             PG8_LDB(B0, 0, 0); PG8_SCHED; PG8_LDA(At, 0, 0); PG8_STAGE(PG8_SA(1, 1), a1 + hstep, voffA);
;             PG8_WAIT_L(8); PG8_BAR; PG8_WAIT_L(0); PG8_MMA(0, 0, At, B0); PG8_BAR; PG8_SCHED;
;             PG8_LDB(B1, 0, 1); PG8_STAGE(PG8_SB(0, 0), b2, voffB);
;             PG8_BAR; PG8_WAIT_L(0); PG8_MMA(0, 1, At, B1); PG8_BAR;
;             PG8_LDA(At, 0, 1); PG8_STAGE(PG8_SA(0, 0), a2, voffA);
;             PG8_BAR; PG8_WAIT_L(0); PG8_MMA(1, 0, At, B0); PG8_BAR; PG8_SCHED;
;             PG8_STAGE(PG8_SB(0, 1), b2 + hstep, voffB);
;             PG8_WAIT_V(6); PG8_BAR; PG8_MMA(1, 1, At, B1); PG8_BAR;
;             PG8_LDB(B0, 1, 0); PG8_SCHED; PG8_LDA(At, 1, 0); PG8_STAGE(PG8_SA(0, 1), a2 + hstep, voffA);
;             PG8_WAIT_L(8); PG8_BAR; PG8_WAIT_L(0); PG8_MMA(0, 0, At, B0); PG8_BAR; PG8_SCHED;
;             PG8_LDB(B1, 1, 1); PG8_STAGE(PG8_SB(1, 0), b3, voffB);
;             PG8_BAR; PG8_WAIT_L(0); PG8_MMA(0, 1, At, B1); PG8_BAR;
;             PG8_LDA(At, 1, 1); PG8_STAGE(PG8_SA(1, 0), a3, voffA);
;             PG8_BAR; PG8_WAIT_L(0); PG8_MMA(1, 0, At, B0); PG8_BAR; PG8_SCHED;
;             PG8_STAGE(PG8_SB(1, 1), b3 + hstep, voffB);
;             PG8_WAIT_V(6); PG8_BAR; PG8_MMA(1, 1, At, B1); PG8_BAR;
;             }
;         }
;         if constexpr (ALIGN_EPI) { if (wr == 0) PG8_BAR; }
;     __device__ __forceinline__ void operator()(const f32x4 (&acc)[2][2][4][2], const Unit& u, int wr, int wc, int fr, int fq) const {
;         const int row0 = u.pm * BM + wr * 64 + fr, col0 = u.pn * BM + wc * 32 + 8 * fq;
;         const bool act = (u.pn == 3) || (u.pn == 4) || (u.pn == 7) || (u.pn == 8);
;         float rs[2][4];
; #pragma unroll
;         for (int ai = 0; ai < 2; ++ai)
; #pragma unroll
.Lrs_in_skip:
	s_cmp_lg_u32 s45, 12
	s_cselect_b64 vcc, exec, s[8:9]
	s_barrier
	v_mfma_f32_16x16x32_bf16 v[66:69], v[144:147], v[182:185], v[66:69]
	v_mfma_f32_16x16x32_bf16 v[66:69], v[154:157], v[186:189], v[66:69]
	v_mfma_f32_16x16x32_bf16 v[50:53], v[144:147], v[190:193], v[50:53]
	v_mfma_f32_16x16x32_bf16 v[50:53], v[154:157], v[198:201], v[50:53]
	v_mfma_f32_16x16x32_bf16 v[34:37], v[144:147], v[202:205], v[34:37]
	v_mfma_f32_16x16x32_bf16 v[34:37], v[154:157], v[206:209], v[34:37]
	v_mfma_f32_16x16x32_bf16 v[18:21], v[144:147], v[210:213], v[18:21]
	v_mfma_f32_16x16x32_bf16 v[18:21], v[154:157], v[214:217], v[18:21]
	v_mfma_f32_16x16x32_bf16 v[62:65], v[158:161], v[182:185], v[62:65]
	v_mfma_f32_16x16x32_bf16 v[62:65], v[162:165], v[186:189], v[62:65]
	v_mfma_f32_16x16x32_bf16 v[46:49], v[158:161], v[190:193], v[46:49]
	v_mfma_f32_16x16x32_bf16 v[46:49], v[162:165], v[198:201], v[46:49]
	v_mfma_f32_16x16x32_bf16 v[30:33], v[158:161], v[202:205], v[30:33]
	v_mfma_f32_16x16x32_bf16 v[30:33], v[162:165], v[206:209], v[30:33]
	v_mfma_f32_16x16x32_bf16 v[14:17], v[158:161], v[210:213], v[14:17]
	v_mfma_f32_16x16x32_bf16 v[14:17], v[162:165], v[214:217], v[14:17]
	v_mfma_f32_16x16x32_bf16 v[58:61], v[166:169], v[182:185], v[58:61]
	v_mfma_f32_16x16x32_bf16 v[58:61], v[170:173], v[186:189], v[58:61]
	v_mfma_f32_16x16x32_bf16 v[42:45], v[166:169], v[190:193], v[42:45]
	v_mfma_f32_16x16x32_bf16 v[42:45], v[170:173], v[198:201], v[42:45]
	v_mfma_f32_16x16x32_bf16 v[26:29], v[166:169], v[202:205], v[26:29]
	v_mfma_f32_16x16x32_bf16 v[26:29], v[170:173], v[206:209], v[26:29]
	v_mfma_f32_16x16x32_bf16 v[10:13], v[166:169], v[210:213], v[10:13]
	v_mfma_f32_16x16x32_bf16 v[10:13], v[170:173], v[214:217], v[10:13]
	v_mfma_f32_16x16x32_bf16 v[54:57], v[174:177], v[182:185], v[54:57]
	v_mfma_f32_16x16x32_bf16 v[54:57], v[178:181], v[186:189], v[54:57]
	v_mfma_f32_16x16x32_bf16 v[38:41], v[174:177], v[190:193], v[38:41]
	v_mfma_f32_16x16x32_bf16 v[38:41], v[178:181], v[198:201], v[38:41]
	v_mfma_f32_16x16x32_bf16 v[22:25], v[174:177], v[202:205], v[22:25]
	v_mfma_f32_16x16x32_bf16 v[22:25], v[178:181], v[206:209], v[22:25]
	v_mfma_f32_16x16x32_bf16 v[6:9], v[174:177], v[210:213], v[6:9]
	v_mfma_f32_16x16x32_bf16 v[6:9], v[178:181], v[214:217], v[6:9]
	s_cbranch_vccz .Le1in_skip
	s_barrier
.Le1in_skip:
	s_add_i32 s45, s45, 2
	s_add_u32 s42, s42, 0x100
	s_addc_u32 s43, s43, 0
	s_add_u32 s25, s25, 0x100
	s_addc_u32 s39, s39, 0
	s_cmp_gt_u32 s45, 13
	s_cbranch_scc0 .LBB0_93
.LBB0_96:
	s_nop 7
	s_nop 7
	v_lshl_add_u32 v144, s38, 8, v5
	v_ashrrev_i32_e32 v145, 31, v144
	v_lshl_add_u64 v[146:147], v[144:145], 2, s[6:7]
	s_add_i32 s11, s10, -3
	s_and_b32 s11, s11, -6
	s_cmp_eq_u32 s11, 0
	s_cselect_b64 s[12:13], -1, 0
	s_cmp_lg_u32 s11, 0
	s_mov_b32 s11, 0x800000
	s_waitcnt vmcnt(0)
	v_fmamk_f32 v146, v226, 0x3a800000, v231
	v_cmp_gt_f32_e32 vcc, s11, v146
	v_mul_f32_e32 v147, 0x4b800000, v146
	s_nop 0
	v_cndmask_b32_e32 v146, v146, v147, vcc
	v_rsq_f32_e32 v146, v146
	s_nop 0
	v_mul_f32_e32 v147, 0x45800000, v146
	v_cndmask_b32_e32 v146, v146, v147, vcc
	v_pk_mul_f32 v[132:133], v[132:133], v[146:147] op_sel_hi:[1,0]
	v_pk_mul_f32 v[130:131], v[130:131], v[146:147] op_sel_hi:[1,0]
	v_pk_mul_f32 v[128:129], v[128:129], v[146:147] op_sel_hi:[1,0]
	v_pk_mul_f32 v[148:149], v[126:127], v[146:147] op_sel_hi:[1,0]
	s_cbranch_scc1 .LBB0_98
	v_mul_f32_e32 v147, 0xbfb8aa3b, v149
	v_exp_f32_e32 v147, v147
	v_mul_f32_e32 v127, 0xbfb8aa3b, v148
	v_exp_f32_e32 v127, v127
	v_mul_f32_e32 v126, 0xbfb8aa3b, v130
	v_add_f32_e32 v147, 1.0, v147
	v_rcp_f32_e32 v161, v147
	v_mul_f32_e32 v147, 0xbfb8aa3b, v132
	v_add_f32_e32 v127, 1.0, v127
	v_exp_f32_e32 v147, v147
	v_rcp_f32_e32 v160, v127
	v_mul_f32_e32 v127, 0xbfb8aa3b, v131
	v_exp_f32_e32 v126, v126
	v_exp_f32_e32 v127, v127
	v_add_f32_e32 v147, 1.0, v147
	v_rcp_f32_e32 v162, v147
	v_mul_f32_e32 v147, 0xbfb8aa3b, v128
	v_add_f32_e32 v126, 1.0, v126
	v_add_f32_e32 v127, 1.0, v127
	v_exp_f32_e32 v147, v147
	v_rcp_f32_e32 v126, v126
	v_rcp_f32_e32 v127, v127
	v_pk_mul_f32 v[148:149], v[148:149], v[160:161]
	v_add_f32_e32 v147, 1.0, v147
	v_rcp_f32_e32 v164, v147
	v_mul_f32_e32 v147, 0xbfb8aa3b, v133
	v_pk_mul_f32 v[130:131], v[130:131], v[126:127]
	v_mul_f32_e32 v126, 0xbfb8aa3b, v129
	v_exp_f32_e32 v147, v147
	v_exp_f32_e32 v126, v126
	v_add_f32_e32 v147, 1.0, v147
	v_add_f32_e32 v126, 1.0, v126
	v_rcp_f32_e32 v163, v147
	v_rcp_f32_e32 v165, v126
	v_pk_mul_f32 v[132:133], v[132:133], v[162:163]
	v_pk_mul_f32 v[128:129], v[128:129], v[164:165]

; template <class Epi, class Sched, bool ALIGN_EPI = false, bool SP2 = false>
; __device__ __forceinline__ void gemm_phase(PG8_LAS unsigned char* lds, const Gemm g, const Sched& S, const Epi& E, const int tid_in) {
;     ...
;             PG8_WAIT_V(8); PG8_WAIT_L(0); PG8_BAR; PG8_MMA(0, 0, At, B0); PG8_MMA(0, 1, At, B1); PG8_BAR; PG8_SCHED;
;             PG8_LDA(At, 1, 1); PG8_STAGE(PG8_SB(1, 0), b3, voffB); PG8_STAGE(PG8_SB(1, 1), b3 + hstep, voffB); PG8_STAGE(PG8_SA(1, 0), a3, voffA);
;             PG8_WAIT_V(8); PG8_WAIT_L(0); PG8_BAR; PG8_MMA(1, 0, At, B0); PG8_MMA(1, 1, At, B1); PG8_BAR; PG8_SCHED;
;             } else {
;             PG8_LDB(B0, 0, 0); PG8_SCHED; PG8_LDA(At, 0, 0); PG8_STAGE(PG8_SA(1, 1), a1 + hstep, voffA);
;             PG8_WAIT_L(8); PG8_BAR; PG8_WAIT_L(0); PG8_MMA(0, 0, At, B0); PG8_BAR; PG8_SCHED;
;             PG8_LDB(B1, 0, 1); PG8_STAGE(PG8_SB(0, 0), b2, voffB);
;             PG8_BAR; PG8_WAIT_L(0); PG8_MMA(0, 1, At, B1); PG8_BAR;
;             PG8_LDA(At, 0, 1); PG8_STAGE(PG8_SA(0, 0), a2, voffA);
;             PG8_BAR; PG8_WAIT_L(0); PG8_MMA(1, 0, At, B0); PG8_BAR; PG8_SCHED;
;             PG8_STAGE(PG8_SB(0, 1), b2 + hstep, voffB);
;             PG8_WAIT_V(6); PG8_BAR; PG8_MMA(1, 1, At, B1); PG8_BAR;
;             PG8_LDB(B0, 1, 0); PG8_SCHED; PG8_LDA(At, 1, 0); PG8_STAGE(PG8_SA(0, 1), a2 + hstep, voffA);
;             PG8_WAIT_L(8); PG8_BAR; PG8_WAIT_L(0); PG8_MMA(0, 0, At, B0); PG8_BAR; PG8_SCHED;
;             PG8_LDB(B1, 1, 1); PG8_STAGE(PG8_SB(1, 0), b3, voffB);
;             PG8_BAR; PG8_WAIT_L(0); PG8_MMA(0, 1, At, B1); PG8_BAR;
;             PG8_LDA(At, 1, 1); PG8_STAGE(PG8_SA(1, 0), a3, voffA);
;             PG8_BAR; PG8_WAIT_L(0); PG8_MMA(1, 0, At, B0); PG8_BAR; PG8_SCHED;
;             PG8_STAGE(PG8_SB(1, 1), b3 + hstep, voffB);
;             PG8_WAIT_V(6); PG8_BAR; PG8_MMA(1, 1, At, B1); PG8_BAR;
;             }
;         }
;         if constexpr (ALIGN_EPI) { if (wr == 0) PG8_BAR; }
;     __device__ __forceinline__ void operator()(const f32x4 (&acc)[2][2][4][2], const Unit& u, int wr, int wc, int fr, int fq) const {
;         if (dry) { asm volatile("" :: "v"(acc[0][0][0][0]), "v"(acc[1][1][3][1])); return; }
;         const int row0 = u.pm * BM + wr * 64 + fr, col0 = u.pn * HALF + wc * 32 + 8 * fq;
;         float rs[2][4];
; #pragma unroll
;         for (int ai = 0; ai < 2; ++ai)
; #pragma unroll
.Lrs_gu_skip:
	s_cmp_lg_u32 s45, 12
	s_cselect_b64 vcc, exec, s[8:9]
	s_barrier
	v_mfma_f32_16x16x32_bf16 v[66:69], v[150:153], v[182:185], v[66:69]
	v_mfma_f32_16x16x32_bf16 v[66:69], v[154:157], v[186:189], v[66:69]
	v_mfma_f32_16x16x32_bf16 v[50:53], v[150:153], v[190:193], v[50:53]
	v_mfma_f32_16x16x32_bf16 v[50:53], v[154:157], v[198:201], v[50:53]
	v_mfma_f32_16x16x32_bf16 v[34:37], v[150:153], v[202:205], v[34:37]
	v_mfma_f32_16x16x32_bf16 v[34:37], v[154:157], v[206:209], v[34:37]
	v_mfma_f32_16x16x32_bf16 v[18:21], v[150:153], v[210:213], v[18:21]
	v_mfma_f32_16x16x32_bf16 v[18:21], v[154:157], v[214:217], v[18:21]
	v_mfma_f32_16x16x32_bf16 v[62:65], v[158:161], v[182:185], v[62:65]
	v_mfma_f32_16x16x32_bf16 v[62:65], v[162:165], v[186:189], v[62:65]
	v_mfma_f32_16x16x32_bf16 v[46:49], v[158:161], v[190:193], v[46:49]
	v_mfma_f32_16x16x32_bf16 v[46:49], v[162:165], v[198:201], v[46:49]
	v_mfma_f32_16x16x32_bf16 v[30:33], v[158:161], v[202:205], v[30:33]
	v_mfma_f32_16x16x32_bf16 v[30:33], v[162:165], v[206:209], v[30:33]
	v_mfma_f32_16x16x32_bf16 v[14:17], v[158:161], v[210:213], v[14:17]
	v_mfma_f32_16x16x32_bf16 v[14:17], v[162:165], v[214:217], v[14:17]
	v_mfma_f32_16x16x32_bf16 v[58:61], v[166:169], v[182:185], v[58:61]
	v_mfma_f32_16x16x32_bf16 v[58:61], v[170:173], v[186:189], v[58:61]
	v_mfma_f32_16x16x32_bf16 v[42:45], v[166:169], v[190:193], v[42:45]
	v_mfma_f32_16x16x32_bf16 v[42:45], v[170:173], v[198:201], v[42:45]
	v_mfma_f32_16x16x32_bf16 v[26:29], v[166:169], v[202:205], v[26:29]
	v_mfma_f32_16x16x32_bf16 v[26:29], v[170:173], v[206:209], v[26:29]
	v_mfma_f32_16x16x32_bf16 v[10:13], v[166:169], v[210:213], v[10:13]
	v_mfma_f32_16x16x32_bf16 v[10:13], v[170:173], v[214:217], v[10:13]
	v_mfma_f32_16x16x32_bf16 v[54:57], v[174:177], v[182:185], v[54:57]
	v_mfma_f32_16x16x32_bf16 v[54:57], v[178:181], v[186:189], v[54:57]
	v_mfma_f32_16x16x32_bf16 v[38:41], v[174:177], v[190:193], v[38:41]
	v_mfma_f32_16x16x32_bf16 v[38:41], v[178:181], v[198:201], v[38:41]
	v_mfma_f32_16x16x32_bf16 v[22:25], v[174:177], v[202:205], v[22:25]
	v_mfma_f32_16x16x32_bf16 v[22:25], v[178:181], v[206:209], v[22:25]
	v_mfma_f32_16x16x32_bf16 v[6:9], v[174:177], v[210:213], v[6:9]
	v_mfma_f32_16x16x32_bf16 v[6:9], v[178:181], v[214:217], v[6:9]
	s_cbranch_vccz .Le1gu_skip
	s_barrier
.Le1gu_skip:
	s_add_i32 s45, s45, 2
	s_add_u32 s10, s10, 0x100
	s_addc_u32 s11, s11, 0
	s_add_u32 s43, s43, 0x100
	s_addc_u32 s44, s44, 0
	s_cmp_gt_u32 s45, 13
	s_cbranch_scc0 .LBB0_154
.LBB0_157:
	s_nop 7
	s_nop 7
	v_lshl_add_u32 v144, s40, 8, v5
	v_ashrrev_i32_e32 v145, 31, v144
	v_lshl_add_u64 v[162:163], v[144:145], 2, s[6:7]
	s_mov_b32 s12, 0x800000
	v_pk_mul_f32 v[124:125], v[132:133], v[124:125]
	v_pk_mul_f32 v[122:123], v[130:131], v[122:123]
	v_pk_mul_f32 v[118:119], v[126:127], v[118:119]
	v_lshl_or_b32 v162, s31, 7, v147
	v_pk_mul_f32 v[120:121], v[128:129], v[120:121]
	v_ashrrev_i32_e32 v163, 31, v162
	s_movk_i32 s13, 0x1600
	v_pk_mul_f32 v[104:105], v[108:109], v[104:105]
	v_pk_mul_f32 v[102:103], v[106:107], v[102:103]
	v_or_b32_e32 v160, 16, v144
	v_pk_mul_f32 v[112:113], v[116:117], v[112:113]
	v_pk_mul_f32 v[110:111], v[114:115], v[110:111]
	v_pk_mul_f32 v[90:91], v[98:99], v[90:91]
	v_or_b32_e32 v158, 32, v144
	v_pk_mul_f32 v[92:93], v[100:101], v[92:93]
	v_pk_mul_f32 v[88:89], v[96:97], v[88:89]
	v_pk_mul_f32 v[86:87], v[94:95], v[86:87]
	v_pk_mul_f32 v[74:75], v[82:83], v[74:75]
	v_or_b32_e32 v156, 48, v144
	v_pk_mul_f32 v[76:77], v[84:85], v[76:77]
	v_pk_mul_f32 v[72:73], v[80:81], v[72:73]
	v_pk_mul_f32 v[70:71], v[78:79], v[70:71]
	v_pk_mul_f32 v[58:59], v[66:67], v[58:59]
	v_add_u32_e32 v154, 0x80, v144
	v_pk_mul_f32 v[60:61], v[68:69], v[60:61]
	v_pk_mul_f32 v[56:57], v[64:65], v[56:57]
	v_pk_mul_f32 v[54:55], v[62:63], v[54:55]
	v_pk_mul_f32 v[42:43], v[50:51], v[42:43]
	v_add_u32_e32 v152, 0x90, v144
	v_pk_mul_f32 v[44:45], v[52:53], v[44:45]
	v_pk_mul_f32 v[40:41], v[48:49], v[40:41]
	v_pk_mul_f32 v[38:39], v[46:47], v[38:39]
	v_pk_mul_f32 v[26:27], v[34:35], v[26:27]
	v_add_u32_e32 v150, 0xa0, v144
	v_pk_mul_f32 v[28:29], v[36:37], v[28:29]
	v_pk_mul_f32 v[24:25], v[32:33], v[24:25]
	v_pk_mul_f32 v[22:23], v[30:31], v[22:23]
	v_pk_mul_f32 v[10:11], v[18:19], v[10:11]
	v_add_u32_e32 v145, 0xb0, v144
	v_pk_mul_f32 v[12:13], v[20:21], v[12:13]
	v_pk_mul_f32 v[8:9], v[16:17], v[8:9]
	v_pk_mul_f32 v[6:7], v[14:15], v[6:7]
	s_waitcnt vmcnt(0)
; __device__ __forceinline__ unsigned cvt2_bf16(float lo, float hi) { const f32x2n v = {lo, hi}; return __builtin_bit_cast(unsigned, __builtin_convertvector(v, bf16x2n)); }
;     __device__ __forceinline__ void operator()(const f32x4 (&acc)[2][2][4][2], const Unit& u, int wr, int wc, int fr, int fq) const {
;     ...
;             for (int m = 0; m < 4; ++m) rs[ai][m] = rowss[row0 + ai * HALF + m * 16];
; #pragma unroll
;         for (int ai = 0; ai < 2; ++ai)
; #pragma unroll
;             for (int m = 0; m < 4; ++m) {
;                 const int row = row0 + ai * HALF + m * 16;
;                 const float ms = rs[ai][m] * (1.0f / 1024.0f) + RMS_EPS, c1 = -1.4426950408889634f * rsqrtf(ms);
;                 const f32x4 g0 = acc[ai][0][m][0], g1 = acc[ai][0][m][1], u0 = acc[ai][1][m][0], u1 = acc[ai][1][m][1];
;                 const f32x4 t0 = g0 * c1, t1 = g1 * c1; f32x4 e0, e1, i0, i1;
; #pragma unroll
;                 for (int e = 0; e < 4; ++e) { e0[e] = __builtin_amdgcn_exp2f(t0[e]); e1[e] = __builtin_amdgcn_exp2f(t1[e]); }
;                 const f32x4 d0 = e0 * ms + ms, d1 = e1 * ms + ms;
; #pragma unroll
;                 for (int e = 0; e < 4; ++e) { i0[e] = __builtin_amdgcn_rcpf(d0[e]); i1[e] = __builtin_amdgcn_rcpf(d1[e]); }
;                 const f32x4 h0 = (g0 * u0) * i0, h1 = (g1 * u1) * i1;
;                 u32x4 w; w.x = cvt2_bf16(h0[0], h0[1]); w.y = cvt2_bf16(h0[2], h0[3]); w.z = cvt2_bf16(h1[0], h1[1]); w.w = cvt2_bf16(h1[2], h1[3]);
;                 *(u32x4*)(H + (size_t)row * ldh + col0) = w;
;             }
	v_fmamk_f32 v164, v226, 0x3a800000, v231
	v_cmp_gt_f32_e32 vcc, s12, v164
	v_mul_f32_e32 v161, 0x4b800000, v164
	s_nop 0
	v_cndmask_b32_e32 v161, v164, v161, vcc
	v_rsq_f32_e32 v161, v161
	s_nop 0
	v_mul_f32_e32 v165, 0x45800000, v161
	v_cndmask_b32_e32 v161, v161, v165, vcc
	v_mul_f32_e32 v166, 0xbfb8aa3b, v161
	v_pk_mul_f32 v[168:169], v[132:133], v[166:167] op_sel_hi:[1,0]
	v_pk_mul_f32 v[170:171], v[130:131], v[166:167] op_sel_hi:[1,0]
	v_pk_mul_f32 v[172:173], v[128:129], v[166:167] op_sel_hi:[1,0]
	v_pk_mul_f32 v[166:167], v[126:127], v[166:167] op_sel_hi:[1,0]
	v_exp_f32_e32 v170, v170
	v_exp_f32_e32 v166, v166
	v_exp_f32_e32 v171, v171
	v_exp_f32_e32 v167, v167
	v_exp_f32_e32 v168, v168
	v_exp_f32_e32 v172, v172
	v_exp_f32_e32 v169, v169
	v_exp_f32_e32 v173, v173
	v_pk_fma_f32 v[170:171], v[164:165], v[170:171], v[164:165] op_sel_hi:[0,1,0]
	v_pk_fma_f32 v[168:169], v[164:165], v[168:169], v[164:165] op_sel_hi:[0,1,0]
	v_pk_fma_f32 v[172:173], v[164:165], v[172:173], v[164:165] op_sel_hi:[0,1,0]
	v_pk_fma_f32 v[164:165], v[164:165], v[166:167], v[164:165] op_sel_hi:[0,1,0]
	v_rcp_f32_e32 v166, v170
	v_rcp_f32_e32 v164, v164
	v_rcp_f32_e32 v167, v171
	v_rcp_f32_e32 v165, v165
	v_rcp_f32_e32 v168, v168
	v_rcp_f32_e32 v169, v169
	v_rcp_f32_e32 v170, v172
	v_rcp_f32_e32 v171, v173
	v_pk_mul_f32 v[122:123], v[122:123], v[166:167]
	v_pk_mul_f32 v[124:125], v[124:125], v[168:169]
	v_pk_mul_f32 v[118:119], v[118:119], v[164:165]
	v_pk_mul_f32 v[120:121], v[120:121], v[170:171]
	v_cvt_pk_bf16_f32 v122, v122, v123
	v_cvt_pk_bf16_f32 v123, v124, v125
	v_cvt_pk_bf16_f32 v124, v118, v119
	v_mov_b64_e32 v[118:119], s[86:87]
	v_cvt_pk_bf16_f32 v125, v120, v121
	v_mad_i64_i32 v[126:127], s[10:11], v144, s13, v[118:119]
	v_lshlrev_b64 v[120:121], 1, v[162:163]
	v_lshl_add_u64 v[126:127], v[126:127], 0, v[120:121]
	global_store_dwordx4 v[126:127], v[122:125], off
	s_nop 1
	v_fmamk_f32 v122, v227, 0x3a800000, v231
	v_cmp_gt_f32_e32 vcc, s12, v122
	v_mul_f32_e32 v123, 0x4b800000, v122
	s_nop 0
	v_cndmask_b32_e32 v123, v122, v123, vcc
	v_rsq_f32_e32 v123, v123
	s_nop 0
	v_mul_f32_e32 v124, 0x45800000, v123
	v_cndmask_b32_e32 v123, v123, v124, vcc
	v_mul_f32_e32 v124, 0xbfb8aa3b, v123
	v_pk_mul_f32 v[126:127], v[116:117], v[124:125] op_sel_hi:[1,0]
	v_pk_mul_f32 v[128:129], v[114:115], v[124:125] op_sel_hi:[1,0]
	v_pk_mul_f32 v[130:131], v[108:109], v[124:125] op_sel_hi:[1,0]
	v_pk_mul_f32 v[124:125], v[106:107], v[124:125] op_sel_hi:[1,0]
	v_exp_f32_e32 v128, v128
	v_exp_f32_e32 v124, v124
	v_exp_f32_e32 v129, v129
	v_exp_f32_e32 v125, v125
	v_exp_f32_e32 v126, v126
	v_exp_f32_e32 v130, v130
	v_exp_f32_e32 v127, v127
	v_exp_f32_e32 v131, v131
	v_pk_fma_f32 v[132:133], v[122:123], v[126:127], v[122:123] op_sel_hi:[0,1,0]
	v_pk_fma_f32 v[126:127], v[122:123], v[128:129], v[122:123] op_sel_hi:[0,1,0]
	v_pk_fma_f32 v[130:131], v[122:123], v[130:131], v[122:123] op_sel_hi:[0,1,0]
	v_pk_fma_f32 v[122:123], v[122:123], v[124:125], v[122:123] op_sel_hi:[0,1,0]
	v_rcp_f32_e32 v122, v122
	v_rcp_f32_e32 v123, v123
	v_rcp_f32_e32 v124, v130
	v_rcp_f32_e32 v125, v131
	v_rcp_f32_e32 v126, v126
	v_rcp_f32_e32 v127, v127
	v_rcp_f32_e32 v128, v132
	v_rcp_f32_e32 v129, v133
	v_pk_mul_f32 v[106:107], v[104:105], v[124:125]
	v_pk_mul_f32 v[104:105], v[102:103], v[122:123]
	v_pk_mul_f32 v[110:111], v[110:111], v[126:127]
	v_pk_mul_f32 v[112:113], v[112:113], v[128:129]
	v_cvt_pk_bf16_f32 v104, v104, v105
	v_cvt_pk_bf16_f32 v105, v106, v107
	v_mad_i64_i32 v[106:107], s[10:11], v160, s13, v[118:119]
	v_cvt_pk_bf16_f32 v102, v110, v111
	v_cvt_pk_bf16_f32 v103, v112, v113
	v_lshl_add_u64 v[106:107], v[106:107], 0, v[120:121]
	global_store_dwordx4 v[106:107], v[102:105], off
	s_nop 1
	v_fmamk_f32 v102, v228, 0x3a800000, v231
	v_cmp_gt_f32_e32 vcc, s12, v102
	v_mul_f32_e32 v103, 0x4b800000, v102
	s_nop 0
	v_cndmask_b32_e32 v103, v102, v103, vcc
	v_rsq_f32_e32 v103, v103
	s_nop 0
	v_mul_f32_e32 v104, 0x45800000, v103
	v_cndmask_b32_e32 v103, v103, v104, vcc
	v_mul_f32_e32 v104, 0xbfb8aa3b, v103
	v_pk_mul_f32 v[108:109], v[98:99], v[104:105] op_sel_hi:[1,0]
	v_pk_mul_f32 v[106:107], v[100:101], v[104:105] op_sel_hi:[1,0]
	v_pk_mul_f32 v[110:111], v[96:97], v[104:105] op_sel_hi:[1,0]
	v_pk_mul_f32 v[104:105], v[94:95], v[104:105] op_sel_hi:[1,0]
	v_exp_f32_e32 v108, v108
	v_exp_f32_e32 v109, v109
	v_exp_f32_e32 v104, v104
	v_exp_f32_e32 v105, v105
	v_exp_f32_e32 v106, v106
	v_exp_f32_e32 v110, v110
	v_exp_f32_e32 v107, v107
	v_exp_f32_e32 v111, v111
	v_pk_fma_f32 v[108:109], v[102:103], v[108:109], v[102:103] op_sel_hi:[0,1,0]
	v_pk_fma_f32 v[106:107], v[102:103], v[106:107], v[102:103] op_sel_hi:[0,1,0]
	v_pk_fma_f32 v[110:111], v[102:103], v[110:111], v[102:103] op_sel_hi:[0,1,0]
	v_pk_fma_f32 v[102:103], v[102:103], v[104:105], v[102:103] op_sel_hi:[0,1,0]
	v_rcp_f32_e32 v104, v108
	v_rcp_f32_e32 v105, v109
	v_rcp_f32_e32 v102, v102
	v_rcp_f32_e32 v103, v103
	v_rcp_f32_e32 v106, v106
	v_rcp_f32_e32 v108, v110
	v_rcp_f32_e32 v107, v107
	v_rcp_f32_e32 v109, v111
	v_pk_mul_f32 v[90:91], v[90:91], v[104:105]
	v_pk_mul_f32 v[92:93], v[92:93], v[106:107]
	v_pk_mul_f32 v[94:95], v[88:89], v[108:109]
	v_pk_mul_f32 v[88:89], v[86:87], v[102:103]
	v_cvt_pk_bf16_f32 v86, v90, v91
	v_mad_i64_i32 v[90:91], s[10:11], v158, s13, v[118:119]
	v_cvt_pk_bf16_f32 v87, v92, v93
	v_cvt_pk_bf16_f32 v88, v88, v89
	v_cvt_pk_bf16_f32 v89, v94, v95
	v_lshl_add_u64 v[90:91], v[90:91], 0, v[120:121]
	global_store_dwordx4 v[90:91], v[86:89], off
	s_nop 1
	v_fmamk_f32 v86, v229, 0x3a800000, v231
	v_cmp_gt_f32_e32 vcc, s12, v86
	v_mul_f32_e32 v87, 0x4b800000, v86
	s_nop 0
	v_cndmask_b32_e32 v87, v86, v87, vcc
; __device__ __forceinline__ unsigned cvt2_bf16(float lo, float hi) { const f32x2n v = {lo, hi}; return __builtin_bit_cast(unsigned, __builtin_convertvector(v, bf16x2n)); }
;     __device__ __forceinline__ void operator()(const f32x4 (&acc)[2][2][4][2], const Unit& u, int wr, int wc, int fr, int fq) const {
;     ...
;         for (int ai = 0; ai < 2; ++ai)
; #pragma unroll
;             for (int m = 0; m < 4; ++m) {
;                 const int row = row0 + ai * HALF + m * 16;
;                 const float ms = rs[ai][m] * (1.0f / 1024.0f) + RMS_EPS, c1 = -1.4426950408889634f * rsqrtf(ms);
;                 const f32x4 g0 = acc[ai][0][m][0], g1 = acc[ai][0][m][1], u0 = acc[ai][1][m][0], u1 = acc[ai][1][m][1];
;                 const f32x4 t0 = g0 * c1, t1 = g1 * c1; f32x4 e0, e1, i0, i1;
; #pragma unroll
;                 for (int e = 0; e < 4; ++e) { e0[e] = __builtin_amdgcn_exp2f(t0[e]); e1[e] = __builtin_amdgcn_exp2f(t1[e]); }
;                 const f32x4 d0 = e0 * ms + ms, d1 = e1 * ms + ms;
; #pragma unroll
;                 for (int e = 0; e < 4; ++e) { i0[e] = __builtin_amdgcn_rcpf(d0[e]); i1[e] = __builtin_amdgcn_rcpf(d1[e]); }
;                 const f32x4 h0 = (g0 * u0) * i0, h1 = (g1 * u1) * i1;
;                 u32x4 w; w.x = cvt2_bf16(h0[0], h0[1]); w.y = cvt2_bf16(h0[2], h0[3]); w.z = cvt2_bf16(h1[0], h1[1]); w.w = cvt2_bf16(h1[2], h1[3]);
;                 *(u32x4*)(H + (size_t)row * ldh + col0) = w;
	v_rsq_f32_e32 v87, v87
	s_nop 0
	v_mul_f32_e32 v88, 0x45800000, v87
	v_cndmask_b32_e32 v87, v87, v88, vcc
	v_mul_f32_e32 v88, 0xbfb8aa3b, v87
	v_pk_mul_f32 v[92:93], v[82:83], v[88:89] op_sel_hi:[1,0]
	v_pk_mul_f32 v[90:91], v[84:85], v[88:89] op_sel_hi:[1,0]
	v_pk_mul_f32 v[94:95], v[80:81], v[88:89] op_sel_hi:[1,0]
	v_pk_mul_f32 v[88:89], v[78:79], v[88:89] op_sel_hi:[1,0]
	v_exp_f32_e32 v92, v92
	v_exp_f32_e32 v93, v93
	v_exp_f32_e32 v88, v88
	v_exp_f32_e32 v89, v89
	v_exp_f32_e32 v90, v90
	v_exp_f32_e32 v94, v94
	v_exp_f32_e32 v91, v91
	v_exp_f32_e32 v95, v95
	v_pk_fma_f32 v[92:93], v[86:87], v[92:93], v[86:87] op_sel_hi:[0,1,0]
	v_pk_fma_f32 v[90:91], v[86:87], v[90:91], v[86:87] op_sel_hi:[0,1,0]
	v_pk_fma_f32 v[94:95], v[86:87], v[94:95], v[86:87] op_sel_hi:[0,1,0]
	v_pk_fma_f32 v[86:87], v[86:87], v[88:89], v[86:87] op_sel_hi:[0,1,0]
	v_rcp_f32_e32 v88, v92
	v_rcp_f32_e32 v89, v93
	v_rcp_f32_e32 v86, v86
	v_rcp_f32_e32 v87, v87
	v_rcp_f32_e32 v90, v90
	v_rcp_f32_e32 v92, v94
	v_rcp_f32_e32 v91, v91
	v_rcp_f32_e32 v93, v95
	v_pk_mul_f32 v[74:75], v[74:75], v[88:89]
	v_pk_mul_f32 v[76:77], v[76:77], v[90:91]
	v_pk_mul_f32 v[78:79], v[72:73], v[92:93]
	v_pk_mul_f32 v[72:73], v[70:71], v[86:87]
	v_cvt_pk_bf16_f32 v70, v74, v75
	v_mad_i64_i32 v[74:75], s[10:11], v156, s13, v[118:119]
	v_cvt_pk_bf16_f32 v71, v76, v77
	v_cvt_pk_bf16_f32 v72, v72, v73
	v_cvt_pk_bf16_f32 v73, v78, v79
	v_lshl_add_u64 v[74:75], v[74:75], 0, v[120:121]
	global_store_dwordx4 v[74:75], v[70:73], off
	s_nop 1
	v_fmamk_f32 v70, v238, 0x3a800000, v231
	v_cmp_gt_f32_e32 vcc, s12, v70
	v_mul_f32_e32 v71, 0x4b800000, v70
	s_nop 0
	v_cndmask_b32_e32 v71, v70, v71, vcc
	v_rsq_f32_e32 v71, v71
	s_nop 0
	v_mul_f32_e32 v72, 0x45800000, v71
	v_cndmask_b32_e32 v71, v71, v72, vcc
	v_mul_f32_e32 v72, 0xbfb8aa3b, v71
	v_pk_mul_f32 v[76:77], v[66:67], v[72:73] op_sel_hi:[1,0]
	v_pk_mul_f32 v[74:75], v[68:69], v[72:73] op_sel_hi:[1,0]
	v_pk_mul_f32 v[78:79], v[64:65], v[72:73] op_sel_hi:[1,0]
	v_pk_mul_f32 v[72:73], v[62:63], v[72:73] op_sel_hi:[1,0]
	v_exp_f32_e32 v76, v76
	v_exp_f32_e32 v77, v77
	v_exp_f32_e32 v72, v72
	v_exp_f32_e32 v73, v73
	v_exp_f32_e32 v74, v74
	v_exp_f32_e32 v78, v78
	v_exp_f32_e32 v75, v75
	v_exp_f32_e32 v79, v79
	v_pk_fma_f32 v[76:77], v[70:71], v[76:77], v[70:71] op_sel_hi:[0,1,0]
	v_pk_fma_f32 v[74:75], v[70:71], v[74:75], v[70:71] op_sel_hi:[0,1,0]
	v_pk_fma_f32 v[78:79], v[70:71], v[78:79], v[70:71] op_sel_hi:[0,1,0]
	v_pk_fma_f32 v[70:71], v[70:71], v[72:73], v[70:71] op_sel_hi:[0,1,0]
	v_rcp_f32_e32 v72, v76
	v_rcp_f32_e32 v73, v77
	v_rcp_f32_e32 v70, v70
	v_rcp_f32_e32 v71, v71
	v_rcp_f32_e32 v74, v74
	v_rcp_f32_e32 v76, v78
	v_rcp_f32_e32 v75, v75
	v_rcp_f32_e32 v77, v79
	v_pk_mul_f32 v[58:59], v[58:59], v[72:73]
	v_pk_mul_f32 v[60:61], v[60:61], v[74:75]
	v_pk_mul_f32 v[62:63], v[56:57], v[76:77]
	v_pk_mul_f32 v[56:57], v[54:55], v[70:71]
	v_cvt_pk_bf16_f32 v54, v58, v59
	v_mad_i64_i32 v[58:59], s[10:11], v154, s13, v[118:119]
	v_cvt_pk_bf16_f32 v55, v60, v61
	v_cvt_pk_bf16_f32 v56, v56, v57
	v_cvt_pk_bf16_f32 v57, v62, v63
	v_lshl_add_u64 v[58:59], v[58:59], 0, v[120:121]
	global_store_dwordx4 v[58:59], v[54:57], off
	s_nop 1
	v_fmamk_f32 v54, v239, 0x3a800000, v231
	v_cmp_gt_f32_e32 vcc, s12, v54
	v_mul_f32_e32 v55, 0x4b800000, v54
	s_nop 0
	v_cndmask_b32_e32 v55, v54, v55, vcc
	v_rsq_f32_e32 v55, v55
	s_nop 0
	v_mul_f32_e32 v56, 0x45800000, v55
	v_cndmask_b32_e32 v55, v55, v56, vcc
	v_mul_f32_e32 v56, 0xbfb8aa3b, v55
	v_pk_mul_f32 v[60:61], v[50:51], v[56:57] op_sel_hi:[1,0]
	v_pk_mul_f32 v[58:59], v[52:53], v[56:57] op_sel_hi:[1,0]
	v_pk_mul_f32 v[62:63], v[48:49], v[56:57] op_sel_hi:[1,0]
	v_pk_mul_f32 v[56:57], v[46:47], v[56:57] op_sel_hi:[1,0]
	v_exp_f32_e32 v60, v60
	v_exp_f32_e32 v61, v61
	v_exp_f32_e32 v56, v56
	v_exp_f32_e32 v57, v57
	v_exp_f32_e32 v58, v58
	v_exp_f32_e32 v62, v62
	v_exp_f32_e32 v59, v59
	v_exp_f32_e32 v63, v63
	v_pk_fma_f32 v[60:61], v[54:55], v[60:61], v[54:55] op_sel_hi:[0,1,0]
	v_pk_fma_f32 v[58:59], v[54:55], v[58:59], v[54:55] op_sel_hi:[0,1,0]
	v_pk_fma_f32 v[62:63], v[54:55], v[62:63], v[54:55] op_sel_hi:[0,1,0]
	v_pk_fma_f32 v[54:55], v[54:55], v[56:57], v[54:55] op_sel_hi:[0,1,0]
; __device__ __forceinline__ unsigned cvt2_bf16(float lo, float hi) { const f32x2n v = {lo, hi}; return __builtin_bit_cast(unsigned, __builtin_convertvector(v, bf16x2n)); }
;     __device__ __forceinline__ void operator()(const f32x4 (&acc)[2][2][4][2], const Unit& u, int wr, int wc, int fr, int fq) const {
;     ...
;         for (int ai = 0; ai < 2; ++ai)
; #pragma unroll
;             for (int m = 0; m < 4; ++m) {
;                 const int row = row0 + ai * HALF + m * 16;
;                 const float ms = rs[ai][m] * (1.0f / 1024.0f) + RMS_EPS, c1 = -1.4426950408889634f * rsqrtf(ms);
;                 const f32x4 g0 = acc[ai][0][m][0], g1 = acc[ai][0][m][1], u0 = acc[ai][1][m][0], u1 = acc[ai][1][m][1];
;                 const f32x4 t0 = g0 * c1, t1 = g1 * c1; f32x4 e0, e1, i0, i1;
; #pragma unroll
;                 for (int e = 0; e < 4; ++e) { e0[e] = __builtin_amdgcn_exp2f(t0[e]); e1[e] = __builtin_amdgcn_exp2f(t1[e]); }
;                 const f32x4 d0 = e0 * ms + ms, d1 = e1 * ms + ms;
; #pragma unroll
;                 for (int e = 0; e < 4; ++e) { i0[e] = __builtin_amdgcn_rcpf(d0[e]); i1[e] = __builtin_amdgcn_rcpf(d1[e]); }
;                 const f32x4 h0 = (g0 * u0) * i0, h1 = (g1 * u1) * i1;
;                 u32x4 w; w.x = cvt2_bf16(h0[0], h0[1]); w.y = cvt2_bf16(h0[2], h0[3]); w.z = cvt2_bf16(h1[0], h1[1]); w.w = cvt2_bf16(h1[2], h1[3]);
;                 *(u32x4*)(H + (size_t)row * ldh + col0) = w;
;             }
	v_rcp_f32_e32 v56, v60
	v_rcp_f32_e32 v57, v61
	v_rcp_f32_e32 v54, v54
	v_rcp_f32_e32 v55, v55
	v_rcp_f32_e32 v58, v58
	v_rcp_f32_e32 v60, v62
	v_rcp_f32_e32 v59, v59
	v_rcp_f32_e32 v61, v63
	v_pk_mul_f32 v[42:43], v[42:43], v[56:57]
	v_pk_mul_f32 v[44:45], v[44:45], v[58:59]
	v_pk_mul_f32 v[46:47], v[40:41], v[60:61]
	v_pk_mul_f32 v[40:41], v[38:39], v[54:55]
	v_cvt_pk_bf16_f32 v38, v42, v43
	v_mad_i64_i32 v[42:43], s[10:11], v152, s13, v[118:119]
	v_cvt_pk_bf16_f32 v39, v44, v45
	v_cvt_pk_bf16_f32 v40, v40, v41
	v_cvt_pk_bf16_f32 v41, v46, v47
	v_lshl_add_u64 v[42:43], v[42:43], 0, v[120:121]
	global_store_dwordx4 v[42:43], v[38:41], off
	s_nop 1
	v_fmamk_f32 v38, v240, 0x3a800000, v231
	v_cmp_gt_f32_e32 vcc, s12, v38
	v_mul_f32_e32 v39, 0x4b800000, v38
	s_nop 0
	v_cndmask_b32_e32 v39, v38, v39, vcc
	v_rsq_f32_e32 v39, v39
	s_nop 0
	v_mul_f32_e32 v40, 0x45800000, v39
	v_cndmask_b32_e32 v39, v39, v40, vcc
	v_mul_f32_e32 v40, 0xbfb8aa3b, v39
	v_pk_mul_f32 v[44:45], v[34:35], v[40:41] op_sel_hi:[1,0]
	v_pk_mul_f32 v[42:43], v[36:37], v[40:41] op_sel_hi:[1,0]
	v_pk_mul_f32 v[46:47], v[32:33], v[40:41] op_sel_hi:[1,0]
	v_pk_mul_f32 v[40:41], v[30:31], v[40:41] op_sel_hi:[1,0]
	v_exp_f32_e32 v44, v44
	v_exp_f32_e32 v45, v45
	v_exp_f32_e32 v40, v40
	v_exp_f32_e32 v41, v41
	v_exp_f32_e32 v42, v42
	v_exp_f32_e32 v46, v46
	v_exp_f32_e32 v43, v43
	v_exp_f32_e32 v47, v47
	v_pk_fma_f32 v[44:45], v[38:39], v[44:45], v[38:39] op_sel_hi:[0,1,0]
	v_pk_fma_f32 v[42:43], v[38:39], v[42:43], v[38:39] op_sel_hi:[0,1,0]
	v_pk_fma_f32 v[46:47], v[38:39], v[46:47], v[38:39] op_sel_hi:[0,1,0]
	v_pk_fma_f32 v[38:39], v[38:39], v[40:41], v[38:39] op_sel_hi:[0,1,0]
	v_rcp_f32_e32 v40, v44
	v_rcp_f32_e32 v41, v45
	v_rcp_f32_e32 v38, v38
	v_rcp_f32_e32 v39, v39
	v_rcp_f32_e32 v42, v42
	v_rcp_f32_e32 v44, v46
	v_rcp_f32_e32 v43, v43
	v_rcp_f32_e32 v45, v47
	v_pk_mul_f32 v[26:27], v[26:27], v[40:41]
	v_pk_mul_f32 v[28:29], v[28:29], v[42:43]
	v_pk_mul_f32 v[30:31], v[24:25], v[44:45]
	v_pk_mul_f32 v[24:25], v[22:23], v[38:39]
	v_cvt_pk_bf16_f32 v22, v26, v27
	v_mad_i64_i32 v[26:27], s[10:11], v150, s13, v[118:119]
	v_cvt_pk_bf16_f32 v23, v28, v29
	v_cvt_pk_bf16_f32 v24, v24, v25
	v_cvt_pk_bf16_f32 v25, v30, v31
	v_lshl_add_u64 v[26:27], v[26:27], 0, v[120:121]
	global_store_dwordx4 v[26:27], v[22:25], off
	s_nop 1
	v_fmamk_f32 v22, v241, 0x3a800000, v231
	v_cmp_gt_f32_e32 vcc, s12, v22
	v_mul_f32_e32 v23, 0x4b800000, v22
	s_nop 0
	v_cndmask_b32_e32 v23, v22, v23, vcc
	v_rsq_f32_e32 v23, v23
	s_nop 0
	v_mul_f32_e32 v24, 0x45800000, v23
	v_cndmask_b32_e32 v23, v23, v24, vcc
	v_mul_f32_e32 v24, 0xbfb8aa3b, v23
	v_pk_mul_f32 v[28:29], v[18:19], v[24:25] op_sel_hi:[1,0]
	v_pk_mul_f32 v[26:27], v[20:21], v[24:25] op_sel_hi:[1,0]
	v_pk_mul_f32 v[30:31], v[16:17], v[24:25] op_sel_hi:[1,0]
	v_pk_mul_f32 v[24:25], v[14:15], v[24:25] op_sel_hi:[1,0]
	v_exp_f32_e32 v28, v28
	v_exp_f32_e32 v29, v29
	v_exp_f32_e32 v24, v24
	v_exp_f32_e32 v25, v25
	v_exp_f32_e32 v26, v26
	v_exp_f32_e32 v30, v30
	v_exp_f32_e32 v27, v27
	v_exp_f32_e32 v31, v31
	v_pk_fma_f32 v[28:29], v[22:23], v[28:29], v[22:23] op_sel_hi:[0,1,0]
	s_andn2_b64 vcc, exec, s[36:37]
	v_pk_fma_f32 v[26:27], v[22:23], v[26:27], v[22:23] op_sel_hi:[0,1,0]
	v_pk_fma_f32 v[30:31], v[22:23], v[30:31], v[22:23] op_sel_hi:[0,1,0]
	v_pk_fma_f32 v[22:23], v[22:23], v[24:25], v[22:23] op_sel_hi:[0,1,0]
	v_rcp_f32_e32 v24, v28
	v_rcp_f32_e32 v25, v29
	v_rcp_f32_e32 v22, v22
	v_rcp_f32_e32 v23, v23
	v_rcp_f32_e32 v26, v26
	v_rcp_f32_e32 v28, v30
	v_rcp_f32_e32 v27, v27
	v_rcp_f32_e32 v29, v31
	v_pk_mul_f32 v[10:11], v[10:11], v[24:25]
	v_pk_mul_f32 v[12:13], v[12:13], v[26:27]
	v_pk_mul_f32 v[14:15], v[8:9], v[28:29]
	v_pk_mul_f32 v[8:9], v[6:7], v[22:23]
	v_cvt_pk_bf16_f32 v6, v10, v11
	v_mad_i64_i32 v[10:11], s[10:11], v145, s13, v[118:119]
	v_cvt_pk_bf16_f32 v7, v12, v13
	v_cvt_pk_bf16_f32 v8, v8, v9
	v_cvt_pk_bf16_f32 v9, v14, v15
	v_lshl_add_u64 v[10:11], v[10:11], 0, v[120:121]
	s_mov_b64 s[10:11], -1
	global_store_dwordx4 v[10:11], v[6:9], off
	s_cbranch_vccnz .LBB0_150
	s_andn2_b64 vcc, exec, s[4:5]
	s_cbranch_vccnz .LBB0_149
	s_barrier
	s_branch .LBB0_149
